# saddr version plus accumulator zeroing with v_mov_b64 in the P1/P6 unit headers
# baseline (speedup 1.0000x reference)
.LBB0_130:
	s_ashr_i32 s23, s22, 31
	s_lshl_b64 s[24:25], s[22:23], 20
	s_add_u32 s24, s90, s24
	s_addc_u32 s25, s91, s25
	s_and_b64 s[26:27], s[0:1], exec
	s_cselect_b32 s23, s25, s31
	s_cselect_b32 s51, s24, s30
	s_ashr_i32 s21, s20, 31
	s_lshl_b64 s[26:27], s[20:21], 20
	s_add_u32 s26, s2, s26
	s_addc_u32 s27, s3, s27
	s_and_b64 s[36:37], s[0:1], exec
	s_cselect_b32 s21, s27, s35
	s_cselect_b32 s52, s26, s34
	s_add_u32 s30, s30, 0x80080
	s_addc_u32 s31, s31, 0
	s_add_u32 s53, s34, 0x100
	v_mov_b32_e32 v0, 0
	s_addc_u32 s54, s35, 0
	s_mov_b32 s55, -2
	v_mov_b32_e32 v1, v0
	v_mov_b64_e32 v[2:3], 0
	v_mov_b64_e32 v[4:5], 0
	v_mov_b64_e32 v[6:7], 0
	s_waitcnt vmcnt(0)
	v_mov_b64_e32 v[16:17], 0
	v_mov_b64_e32 v[18:19], 0
	v_mov_b64_e32 v[20:21], 0
	v_mov_b64_e32 v[22:23], 0
	v_mov_b64_e32 v[32:33], 0
	v_mov_b64_e32 v[34:35], 0
	v_mov_b64_e32 v[36:37], 0
	v_mov_b64_e32 v[38:39], 0
	v_mov_b64_e32 v[48:49], 0
	v_mov_b64_e32 v[50:51], 0
	v_mov_b64_e32 v[52:53], 0
	v_mov_b64_e32 v[54:55], 0
	v_mov_b64_e32 v[8:9], 0
	v_mov_b64_e32 v[10:11], 0
	v_mov_b64_e32 v[12:13], 0
	v_mov_b64_e32 v[14:15], 0
	v_mov_b64_e32 v[24:25], 0
	v_mov_b64_e32 v[26:27], 0
	v_mov_b64_e32 v[28:29], 0
	v_mov_b64_e32 v[30:31], 0
	v_mov_b64_e32 v[40:41], 0
	v_mov_b64_e32 v[42:43], 0
	v_mov_b64_e32 v[44:45], 0
	v_mov_b64_e32 v[46:47], 0
	v_mov_b64_e32 v[56:57], 0
	v_mov_b64_e32 v[58:59], 0
	v_mov_b64_e32 v[60:61], 0
	v_mov_b64_e32 v[62:63], 0
	v_mov_b64_e32 v[64:65], 0
	v_mov_b64_e32 v[66:67], 0
	v_mov_b64_e32 v[68:69], 0
	v_mov_b64_e32 v[70:71], 0
	v_mov_b64_e32 v[80:81], 0
	v_mov_b64_e32 v[82:83], 0
	v_mov_b64_e32 v[84:85], 0
	v_mov_b64_e32 v[86:87], 0
	v_mov_b64_e32 v[96:97], 0
	v_mov_b64_e32 v[98:99], 0
	v_mov_b64_e32 v[100:101], 0
	v_mov_b64_e32 v[102:103], 0
	v_mov_b64_e32 v[112:113], 0
	v_mov_b64_e32 v[114:115], 0
	v_mov_b64_e32 v[116:117], 0
	v_mov_b64_e32 v[118:119], 0
	v_mov_b64_e32 v[72:73], 0
	v_mov_b64_e32 v[74:75], 0
	v_mov_b64_e32 v[76:77], 0
	v_mov_b64_e32 v[78:79], 0
	v_mov_b64_e32 v[88:89], 0
	v_mov_b64_e32 v[90:91], 0
	v_mov_b64_e32 v[92:93], 0
	v_mov_b64_e32 v[94:95], 0
	v_mov_b64_e32 v[104:105], 0
	v_mov_b64_e32 v[106:107], 0
	v_mov_b64_e32 v[108:109], 0
	v_mov_b64_e32 v[110:111], 0
	v_mov_b64_e32 v[120:121], 0
	v_mov_b64_e32 v[122:123], 0
	v_mov_b64_e32 v[124:125], 0
	v_mov_b64_e32 v[126:127], 0

.LBB0_670:
	s_ashr_i32 s19, s18, 31
	s_lshl_b64 s[20:21], s[18:19], 20
	s_add_u32 s20, s3, s20
	s_addc_u32 s21, s33, s21
	s_and_b64 s[22:23], s[0:1], exec
	s_cselect_b32 s19, s21, s27
	s_cselect_b32 s49, s20, s26
	s_ashr_i32 s17, s16, 31
	s_lshl_b64 s[22:23], s[16:17], 20
	s_add_u32 s22, s34, s22
	s_addc_u32 s23, s35, s23
	s_and_b64 s[30:31], s[0:1], exec
	s_cselect_b32 s17, s23, s29
	s_cselect_b32 s50, s22, s28
	s_add_u32 s26, s26, 0x80080
	s_addc_u32 s27, s27, 0
	s_add_u32 s51, s28, 0x100
	v_mov_b32_e32 v4, 0
	s_addc_u32 s52, s29, 0
	s_mov_b32 s53, -2
	v_mov_b32_e32 v5, v4
	v_mov_b64_e32 v[6:7], 0
	v_mov_b64_e32 v[12:13], 0
	v_mov_b64_e32 v[14:15], 0
	v_mov_b64_e32 v[24:25], 0
	s_waitcnt vmcnt(0)
	v_mov_b64_e32 v[26:27], 0
	v_mov_b64_e32 v[28:29], 0
	v_mov_b64_e32 v[30:31], 0
	v_mov_b64_e32 v[40:41], 0
	v_mov_b64_e32 v[42:43], 0
	v_mov_b64_e32 v[44:45], 0
	v_mov_b64_e32 v[46:47], 0
	v_mov_b64_e32 v[56:57], 0
	v_mov_b64_e32 v[58:59], 0
	v_mov_b64_e32 v[60:61], 0
	v_mov_b64_e32 v[62:63], 0
	v_mov_b64_e32 v[0:1], 0
	v_mov_b64_e32 v[2:3], 0
	v_mov_b64_e32 v[8:9], 0
	v_mov_b64_e32 v[10:11], 0
	v_mov_b64_e32 v[16:17], 0
	v_mov_b64_e32 v[18:19], 0
	v_mov_b64_e32 v[20:21], 0
	v_mov_b64_e32 v[22:23], 0
	v_mov_b64_e32 v[32:33], 0
	v_mov_b64_e32 v[34:35], 0
	v_mov_b64_e32 v[36:37], 0
	v_mov_b64_e32 v[38:39], 0
	v_mov_b64_e32 v[48:49], 0
	v_mov_b64_e32 v[50:51], 0
	v_mov_b64_e32 v[52:53], 0
	v_mov_b64_e32 v[54:55], 0
	v_mov_b64_e32 v[72:73], 0
	v_mov_b64_e32 v[74:75], 0
	v_mov_b64_e32 v[76:77], 0
	v_mov_b64_e32 v[78:79], 0
	v_mov_b64_e32 v[88:89], 0
	v_mov_b64_e32 v[90:91], 0
	v_mov_b64_e32 v[92:93], 0
	v_mov_b64_e32 v[94:95], 0
	v_mov_b64_e32 v[104:105], 0
	v_mov_b64_e32 v[106:107], 0
	v_mov_b64_e32 v[108:109], 0
	v_mov_b64_e32 v[110:111], 0
	v_mov_b64_e32 v[120:121], 0
	v_mov_b64_e32 v[122:123], 0
	v_mov_b64_e32 v[124:125], 0
	v_mov_b64_e32 v[126:127], 0
	v_mov_b64_e32 v[64:65], 0
	v_mov_b64_e32 v[66:67], 0
	v_mov_b64_e32 v[68:69], 0
	v_mov_b64_e32 v[70:71], 0
	v_mov_b64_e32 v[80:81], 0
	v_mov_b64_e32 v[82:83], 0
	v_mov_b64_e32 v[84:85], 0
	v_mov_b64_e32 v[86:87], 0
	v_mov_b64_e32 v[96:97], 0
	v_mov_b64_e32 v[98:99], 0
	v_mov_b64_e32 v[100:101], 0
	v_mov_b64_e32 v[102:103], 0
	v_mov_b64_e32 v[112:113], 0
	v_mov_b64_e32 v[114:115], 0
	v_mov_b64_e32 v[116:117], 0
	v_mov_b64_e32 v[118:119], 0
